# accumulator zeroing with 64 v_mov_b64 per unit instead of 128 v_mov_b32
# speedup vs baseline: 1.0238x; 1.0069x over previous
;     __host__ __device__ bool next(int i, Unit& o) const { if (i != 0) return false; o = u; return true; }
; #define PG8_STAGE(bufoff, gbase, voff) do { _Pragma("unroll") for (int _i = 0; _i < 2; ++_i) \
;         __builtin_amdgcn_global_load_lds((const unsigned*)((const char*)(gbase) + (voff)[_i]), (PG8_LAS unsigned*)(lds + (bufoff) + ldsw + _i * 8192), 16, 0, 0); } while (0)
; #define PG8_LDA(dst, b, h) do { _Pragma("unroll") for (int m = 0; m < 4; ++m) _Pragma("unroll") for (int k = 0; k < 2; ++k) dst[m][k] = *(const PG8_LAS bf16x8*)(lds + PG8_SA(b, h) + aoff + m * 2048 + k * 1024); } while (0)
; #define PG8_LDB(dst, b, h) do { _Pragma("unroll") for (int n = 0; n < 2; ++n) _Pragma("unroll") for (int k = 0; k < 2; ++k) dst[n][k] = *(const PG8_LAS bf16x8*)(lds + PG8_SB(b, h) + boff + n * 2048 + k * 1024); } while (0)
; #define PG8_WAIT_V(n) asm volatile("s_waitcnt vmcnt(" #n ")" ::: "memory")
; template <class Epi, class Sched, bool ALIGN_EPI = false, bool SP2 = false>
; __device__ __forceinline__ void gemm_phase(PG8_LAS unsigned char* lds, const Gemm g, const Sched& S, const Epi& E, const int wid_) {
;     ...
;         const bool has_next = S.next(ui + 1, nxt);
;         const char* nA = has_next ? (const char*)g.A + (size_t)nxt.pm * tstepA : cA; const char* nB = has_next ? (const char*)g.Bt + (size_t)nxt.pn * tstepB : cB;
;         for (int t = 0; t < nt; t += 2) {
;             const bool last = (t == nt - 2);
;             const char* a1 = cA + (size_t)(t + 1) * kstep;
;             const char* a2 = last ? nA : cA + (size_t)(t + 2) * kstep; const char* b2 = last ? nB : cB + (size_t)(t + 2) * kstep;
;             const char* a3 = a2 + kstep; const char* b3 = b2 + kstep;
;             if (last && has_next) S.a_ready(nxt);
;             if constexpr (SP2) {
;             PG8_LDB(B0, 0, 0); PG8_LDB(B1, 0, 1); PG8_SCHED; PG8_LDA(At, 0, 0); PG8_STAGE(PG8_SA(1, 1), a1 + hstepA, voffA);
;             PG8_WAIT_V(8); PG8_WAIT_L(0); PG8_BAR; PG8_MMA(0, 0, At, B0); PG8_MMA(0, 1, At, B1); PG8_BAR; PG8_SCHED;
;     ...
; #pragma unroll
;         for (int a = 0; a < 2; ++a)
; #pragma unroll
;             for (int b = 0; b < 2; ++b)
; #pragma unroll
;                 for (int m = 0; m < 4; ++m)
; #pragma unroll
;                     for (int n = 0; n < 2; ++n) acc[a][b][m][n] = (f32x4){0.f, 0.f, 0.f, 0.f};
;         cur = nxt; cA = nA; cB = nB; ++ui;
.LBB0_379:
	s_add_u32 s49, s38, 0x100
	s_addc_u32 s62, s39, 0
	s_add_u32 s6, s98, 0x80
	s_addc_u32 s7, s99, 0
	s_mov_b32 s38, 0
	s_and_b64 vcc, exec, s[94:95]
	s_cbranch_vccnz .Lprio_a
	s_setprio 1
.Lprio_a:
	v_mov_b64_e32 v[0:1], 0
	v_mov_b64_e32 v[2:3], 0
	v_mov_b64_e32 v[4:5], 0
	v_mov_b64_e32 v[6:7], 0
	v_mov_b64_e32 v[8:9], 0
	v_mov_b64_e32 v[10:11], 0
	v_mov_b64_e32 v[12:13], 0
	v_mov_b64_e32 v[14:15], 0
	v_mov_b64_e32 v[16:17], 0
	v_mov_b64_e32 v[18:19], 0
	v_mov_b64_e32 v[20:21], 0
	v_mov_b64_e32 v[22:23], 0
	v_mov_b64_e32 v[24:25], 0
	v_mov_b64_e32 v[26:27], 0
	v_mov_b64_e32 v[28:29], 0
	v_mov_b64_e32 v[30:31], 0
	v_mov_b64_e32 v[32:33], 0
	v_mov_b64_e32 v[34:35], 0
	v_mov_b64_e32 v[36:37], 0
	v_mov_b64_e32 v[38:39], 0
	v_mov_b64_e32 v[40:41], 0
	v_mov_b64_e32 v[42:43], 0
	v_mov_b64_e32 v[44:45], 0
	v_mov_b64_e32 v[46:47], 0
	v_mov_b64_e32 v[48:49], 0
	v_mov_b64_e32 v[50:51], 0
	v_mov_b64_e32 v[52:53], 0
	v_mov_b64_e32 v[54:55], 0
	v_mov_b64_e32 v[56:57], 0
	v_mov_b64_e32 v[58:59], 0
	v_mov_b64_e32 v[60:61], 0
	v_mov_b64_e32 v[62:63], 0
	v_mov_b64_e32 v[64:65], 0
	v_mov_b64_e32 v[66:67], 0
	v_mov_b64_e32 v[68:69], 0
	v_mov_b64_e32 v[70:71], 0
	v_mov_b64_e32 v[72:73], 0
	v_mov_b64_e32 v[74:75], 0
	v_mov_b64_e32 v[76:77], 0
	v_mov_b64_e32 v[78:79], 0
	v_mov_b64_e32 v[80:81], 0
	v_mov_b64_e32 v[82:83], 0
	v_mov_b64_e32 v[84:85], 0
	v_mov_b64_e32 v[86:87], 0
	v_mov_b64_e32 v[88:89], 0
	v_mov_b64_e32 v[90:91], 0
	v_mov_b64_e32 v[92:93], 0
	v_mov_b64_e32 v[94:95], 0
	v_mov_b64_e32 v[96:97], 0
	v_mov_b64_e32 v[98:99], 0
	v_mov_b64_e32 v[100:101], 0
	v_mov_b64_e32 v[102:103], 0
	v_mov_b64_e32 v[104:105], 0
	v_mov_b64_e32 v[106:107], 0
	v_mov_b64_e32 v[108:109], 0
	v_mov_b64_e32 v[110:111], 0
	v_mov_b64_e32 v[112:113], 0
	v_mov_b64_e32 v[114:115], 0
	v_mov_b64_e32 v[116:117], 0
	v_mov_b64_e32 v[118:119], 0
	v_mov_b64_e32 v[120:121], 0
	v_mov_b64_e32 v[122:123], 0
	v_mov_b64_e32 v[124:125], 0
	v_mov_b64_e32 v[126:127], 0
.LBB0_380:
	s_add_i32 s97, s38, 2
	s_add_u32 s98, s6, 0x80
	s_addc_u32 s39, s7, 0
	s_cmp_eq_u32 s41, s38
	s_cselect_b32 s39, s47, s39
	s_cselect_b32 s38, s46, s98
	s_cselect_b32 s99, s61, s62
	s_cselect_b32 s98, s60, s49
	s_add_i32 vcc_lo, 0, 0x14000
	v_add_u32_e32 v164, s42, v180
	v_add_u32_e32 v176, vcc_lo, v180
	ds_read_b128 v[128:131], v164
	ds_read_b128 v[132:135], v164 offset:1024
	ds_read_b128 v[136:139], v164 offset:2048
	ds_read_b128 v[164:167], v164 offset:3072
	ds_read_b128 v[168:171], v176
	ds_read_b128 v[172:175], v176 offset:1024
	ds_read_b128 v[182:185], v176 offset:2048
	ds_read_b128 v[186:189], v176 offset:3072
	v_lshl_add_u64 v[178:179], s[6:7], 0, v[162:163]
	s_add_i32 m0, s36, 0xc000
	ds_read_b128 v[190:193], v181
	ds_read_b128 v[194:197], v181 offset:1024
	ds_read_b128 v[198:201], v181 offset:2048
	ds_read_b128 v[202:205], v181 offset:3072
	ds_read_b128 v[206:209], v181 offset:4096
	ds_read_b128 v[212:215], v181 offset:5120
	ds_read_b128 v[216:219], v181 offset:6144
	ds_read_b128 v[220:223], v181 offset:7168
	global_load_lds_dwordx4 v[178:179], off
	v_lshl_add_u64 v[178:179], s[6:7], 0, v[160:161]
	s_add_i32 m0, s36, 0xe000
	s_nop 0
	global_load_lds_dwordx4 v[178:179], off
	s_waitcnt vmcnt(8)
	s_waitcnt lgkmcnt(0)
	s_barrier
	s_waitcnt lgkmcnt(0)
	v_mfma_f32_16x16x32_bf16 v[124:127], v[128:131], v[190:193], v[124:127]
	v_mfma_f32_16x16x32_bf16 v[120:123], v[136:139], v[190:193], v[120:123]
	v_mfma_f32_16x16x32_bf16 v[116:119], v[128:131], v[198:201], v[116:119]
	v_mfma_f32_16x16x32_bf16 v[112:115], v[136:139], v[198:201], v[112:115]
	v_mfma_f32_16x16x32_bf16 v[100:103], v[128:131], v[206:209], v[100:103]
	v_mfma_f32_16x16x32_bf16 v[96:99], v[136:139], v[206:209], v[96:99]
	v_mfma_f32_16x16x32_bf16 v[84:87], v[128:131], v[216:219], v[84:87]
	v_mfma_f32_16x16x32_bf16 v[80:83], v[136:139], v[216:219], v[80:83]
	v_mfma_f32_16x16x32_bf16 v[124:127], v[132:135], v[194:197], v[124:127]
	v_mfma_f32_16x16x32_bf16 v[120:123], v[164:167], v[194:197], v[120:123]
	v_mfma_f32_16x16x32_bf16 v[116:119], v[132:135], v[202:205], v[116:119]
	v_mfma_f32_16x16x32_bf16 v[112:115], v[164:167], v[202:205], v[112:115]
	v_mfma_f32_16x16x32_bf16 v[100:103], v[132:135], v[212:215], v[100:103]
	v_mfma_f32_16x16x32_bf16 v[96:99], v[164:167], v[212:215], v[96:99]
	v_mfma_f32_16x16x32_bf16 v[84:87], v[132:135], v[220:223], v[84:87]
	v_mfma_f32_16x16x32_bf16 v[80:83], v[164:167], v[220:223], v[80:83]
	v_mfma_f32_16x16x32_bf16 v[108:111], v[168:171], v[190:193], v[108:111]
	v_mfma_f32_16x16x32_bf16 v[104:107], v[182:185], v[190:193], v[104:107]
	v_mfma_f32_16x16x32_bf16 v[92:95], v[168:171], v[198:201], v[92:95]
	v_mfma_f32_16x16x32_bf16 v[88:91], v[182:185], v[198:201], v[88:91]
	v_mfma_f32_16x16x32_bf16 v[76:79], v[168:171], v[206:209], v[76:79]
	v_mfma_f32_16x16x32_bf16 v[72:75], v[182:185], v[206:209], v[72:75]
	v_mfma_f32_16x16x32_bf16 v[68:71], v[168:171], v[216:219], v[68:71]
	v_mfma_f32_16x16x32_bf16 v[64:67], v[182:185], v[216:219], v[64:67]
	v_mfma_f32_16x16x32_bf16 v[108:111], v[172:175], v[194:197], v[108:111]
	v_mfma_f32_16x16x32_bf16 v[104:107], v[186:189], v[194:197], v[104:107]
	v_mfma_f32_16x16x32_bf16 v[92:95], v[172:175], v[202:205], v[92:95]
	v_mfma_f32_16x16x32_bf16 v[88:91], v[186:189], v[202:205], v[88:91]
	v_mfma_f32_16x16x32_bf16 v[76:79], v[172:175], v[212:215], v[76:79]
	v_mfma_f32_16x16x32_bf16 v[72:75], v[186:189], v[212:215], v[72:75]
	v_mfma_f32_16x16x32_bf16 v[68:71], v[172:175], v[220:223], v[68:71]
	v_mfma_f32_16x16x32_bf16 v[64:67], v[186:189], v[220:223], v[64:67]
	s_barrier
; #define PG8_STAGE(bufoff, gbase, voff) do { _Pragma("unroll") for (int _i = 0; _i < 2; ++_i) \
;         __builtin_amdgcn_global_load_lds((const unsigned*)((const char*)(gbase) + (voff)[_i]), (PG8_LAS unsigned*)(lds + (bufoff) + ldsw + _i * 8192), 16, 0, 0); } while (0)
; #define PG8_LDA(dst, b, h) do { _Pragma("unroll") for (int m = 0; m < 4; ++m) _Pragma("unroll") for (int k = 0; k < 2; ++k) dst[m][k] = *(const PG8_LAS bf16x8*)(lds + PG8_SA(b, h) + aoff + m * 2048 + k * 1024); } while (0)
; #define PG8_LDB(dst, b, h) do { _Pragma("unroll") for (int n = 0; n < 2; ++n) _Pragma("unroll") for (int k = 0; k < 2; ++k) dst[n][k] = *(const PG8_LAS bf16x8*)(lds + PG8_SB(b, h) + boff + n * 2048 + k * 1024); } while (0)
; #define PG8_MMA(ai, bj, At, Bt) do { __builtin_amdgcn_s_setprio(1); _Pragma("unroll") for (int m = 0; m < 4; ++m) _Pragma("unroll") for (int n = 0; n < 2; ++n) _Pragma("unroll") for (int k = 0; k < 2; ++k) \
;         acc[ai][bj][m][n] = __builtin_amdgcn_mfma_f32_16x16x32_bf16(Bt[n][k], At[m][k], acc[ai][bj][m][n], 0, 0, 0); __builtin_amdgcn_s_setprio(0); } while (0)
; #define PG8_WAIT_V(n) asm volatile("s_waitcnt vmcnt(" #n ")" ::: "memory")
; #define PG8_WAIT_L(n) asm volatile("s_waitcnt lgkmcnt(" #n ")" ::: "memory")
; #define PG8_BAR __builtin_amdgcn_s_barrier()
; #define PG8_SCHED __builtin_amdgcn_sched_barrier(0)
; template <class Epi, class Sched, bool ALIGN_EPI = false, bool SP2 = false>
; __device__ __forceinline__ void gemm_phase(PG8_LAS unsigned char* lds, const Gemm g, const Sched& S, const Epi& E, const int wid_) {
;     ...
;             PG8_WAIT_V(8); PG8_WAIT_L(0); PG8_BAR; PG8_MMA(0, 0, At, B0); PG8_MMA(0, 1, At, B1); PG8_BAR; PG8_SCHED;
;             PG8_LDA(At, 0, 1); PG8_STAGE(PG8_SB(0, 0), b2, voffB); PG8_STAGE(PG8_SB(0, 1), b2 + hstepB, voffB); PG8_STAGE(PG8_SA(0, 0), a2, voffA);
;             PG8_WAIT_V(8); PG8_WAIT_L(0); PG8_BAR; PG8_MMA(1, 0, At, B0); PG8_MMA(1, 1, At, B1); PG8_BAR; PG8_SCHED;
;             PG8_LDB(B0, 1, 0); PG8_LDB(B1, 1, 1); PG8_SCHED; PG8_LDA(At, 1, 0); PG8_STAGE(PG8_SA(0, 1), a2 + hstepA, voffA);
;             PG8_WAIT_V(8); PG8_WAIT_L(0); PG8_BAR; PG8_MMA(0, 0, At, B0); PG8_MMA(0, 1, At, B1); PG8_BAR; PG8_SCHED;
	s_add_i32 vcc_hi, s42, s83
	v_lshl_add_u64 v[178:179], s[98:99], 0, v[142:143]
	s_mov_b32 m0, vcc_hi
	ds_read_b128 v[190:193], v181 offset:16384
	ds_read_b128 v[194:197], v181 offset:17408
	ds_read_b128 v[198:201], v181 offset:18432
	ds_read_b128 v[202:205], v181 offset:19456
	ds_read_b128 v[206:209], v181 offset:20480
	ds_read_b128 v[212:215], v181 offset:21504
	ds_read_b128 v[216:219], v181 offset:22528
	ds_read_b128 v[220:223], v181 offset:23552
	global_load_lds_dwordx4 v[178:179], off
	s_add_i32 m0, vcc_hi, 0x2000
	v_lshl_add_u64 v[224:225], s[98:99], 0, v[146:147]
	s_add_u32 s98, s98, s18
	s_addc_u32 s99, s99, 0
	s_add_i32 vcc_lo, vcc_lo, s83
	global_load_lds_dwordx4 v[224:225], off
	v_lshl_add_u64 v[226:227], s[98:99], 0, v[142:143]
	s_mov_b32 m0, vcc_lo
	v_lshl_add_u64 v[228:229], s[98:99], 0, v[146:147]
	global_load_lds_dwordx4 v[226:227], off
	s_add_i32 m0, vcc_lo, 0x2000
	v_lshl_add_u64 v[230:231], s[38:39], 0, v[140:141]
	global_load_lds_dwordx4 v[228:229], off
	s_mov_b32 m0, s36
	v_lshl_add_u64 v[232:233], s[38:39], 0, v[144:145]
	global_load_lds_dwordx4 v[230:231], off
	s_mov_b32 m0, s10
	s_nop 0
	global_load_lds_dwordx4 v[232:233], off
	s_waitcnt vmcnt(8)
	s_waitcnt lgkmcnt(0)
	s_barrier
	s_waitcnt lgkmcnt(0)
	v_mfma_f32_16x16x32_bf16 v[60:63], v[128:131], v[190:193], v[60:63]
	v_mfma_f32_16x16x32_bf16 v[56:59], v[136:139], v[190:193], v[56:59]
	v_mfma_f32_16x16x32_bf16 v[52:55], v[128:131], v[198:201], v[52:55]
	v_mfma_f32_16x16x32_bf16 v[48:51], v[136:139], v[198:201], v[48:51]
	v_mfma_f32_16x16x32_bf16 v[36:39], v[128:131], v[206:209], v[36:39]
	v_mfma_f32_16x16x32_bf16 v[32:35], v[136:139], v[206:209], v[32:35]
	v_mfma_f32_16x16x32_bf16 v[20:23], v[128:131], v[216:219], v[20:23]
	v_mfma_f32_16x16x32_bf16 v[16:19], v[136:139], v[216:219], v[16:19]
	v_mfma_f32_16x16x32_bf16 v[60:63], v[132:135], v[194:197], v[60:63]
	v_mfma_f32_16x16x32_bf16 v[56:59], v[164:167], v[194:197], v[56:59]
	v_mfma_f32_16x16x32_bf16 v[52:55], v[132:135], v[202:205], v[52:55]
	v_mfma_f32_16x16x32_bf16 v[48:51], v[164:167], v[202:205], v[48:51]
	v_mfma_f32_16x16x32_bf16 v[36:39], v[132:135], v[212:215], v[36:39]
	v_mfma_f32_16x16x32_bf16 v[32:35], v[164:167], v[212:215], v[32:35]
	v_mfma_f32_16x16x32_bf16 v[20:23], v[132:135], v[220:223], v[20:23]
	v_mfma_f32_16x16x32_bf16 v[16:19], v[164:167], v[220:223], v[16:19]
	v_mfma_f32_16x16x32_bf16 v[44:47], v[168:171], v[190:193], v[44:47]
	v_mfma_f32_16x16x32_bf16 v[40:43], v[182:185], v[190:193], v[40:43]
	v_mfma_f32_16x16x32_bf16 v[28:31], v[168:171], v[198:201], v[28:31]
	v_mfma_f32_16x16x32_bf16 v[24:27], v[182:185], v[198:201], v[24:27]
	v_mfma_f32_16x16x32_bf16 v[12:15], v[168:171], v[206:209], v[12:15]
	v_mfma_f32_16x16x32_bf16 v[8:11], v[182:185], v[206:209], v[8:11]
	v_mfma_f32_16x16x32_bf16 v[4:7], v[168:171], v[216:219], v[4:7]
	v_mfma_f32_16x16x32_bf16 v[0:3], v[182:185], v[216:219], v[0:3]
	v_mfma_f32_16x16x32_bf16 v[44:47], v[172:175], v[194:197], v[44:47]
	v_mfma_f32_16x16x32_bf16 v[40:43], v[186:189], v[194:197], v[40:43]
	v_mfma_f32_16x16x32_bf16 v[28:31], v[172:175], v[202:205], v[28:31]
	v_mfma_f32_16x16x32_bf16 v[24:27], v[186:189], v[202:205], v[24:27]
	v_mfma_f32_16x16x32_bf16 v[12:15], v[172:175], v[212:215], v[12:15]
	v_mfma_f32_16x16x32_bf16 v[8:11], v[186:189], v[212:215], v[8:11]
	v_mfma_f32_16x16x32_bf16 v[4:7], v[172:175], v[220:223], v[4:7]
	v_mfma_f32_16x16x32_bf16 v[0:3], v[186:189], v[220:223], v[0:3]
	s_barrier
	s_add_i32 s98, 0, 0x18000
	s_add_i32 s99, 0, 0x1c000
	v_add_u32_e32 v164, s98, v180
	v_add_u32_e32 v176, s99, v180
	ds_read_b128 v[128:131], v164
	ds_read_b128 v[132:135], v164 offset:1024
	ds_read_b128 v[136:139], v164 offset:2048
	ds_read_b128 v[164:167], v164 offset:3072
	ds_read_b128 v[168:171], v176
	ds_read_b128 v[172:175], v176 offset:1024
	ds_read_b128 v[182:185], v176 offset:2048
	ds_read_b128 v[186:189], v176 offset:3072
	s_add_u32 s38, s38, s88
	s_addc_u32 s39, s39, 0
	s_mov_b32 m0, s11
	v_lshl_add_u64 v[234:235], s[38:39], 0, v[140:141]
	ds_read_b128 v[190:193], v181 offset:32768
	ds_read_b128 v[194:197], v181 offset:33792
	ds_read_b128 v[198:201], v181 offset:34816
	ds_read_b128 v[202:205], v181 offset:35840
	ds_read_b128 v[206:209], v181 offset:36864
	ds_read_b128 v[212:215], v181 offset:37888
	ds_read_b128 v[216:219], v181 offset:38912
	ds_read_b128 v[220:223], v181 offset:39936
	global_load_lds_dwordx4 v[234:235], off
	v_lshl_add_u64 v[234:235], s[38:39], 0, v[144:145]
	s_mov_b32 m0, s55
	s_nop 0
	global_load_lds_dwordx4 v[234:235], off
	s_waitcnt vmcnt(8)
	s_waitcnt lgkmcnt(0)
	s_barrier
; #define PG8_STAGE(bufoff, gbase, voff) do { _Pragma("unroll") for (int _i = 0; _i < 2; ++_i) \
;         __builtin_amdgcn_global_load_lds((const unsigned*)((const char*)(gbase) + (voff)[_i]), (PG8_LAS unsigned*)(lds + (bufoff) + ldsw + _i * 8192), 16, 0, 0); } while (0)
; #define PG8_LDA(dst, b, h) do { _Pragma("unroll") for (int m = 0; m < 4; ++m) _Pragma("unroll") for (int k = 0; k < 2; ++k) dst[m][k] = *(const PG8_LAS bf16x8*)(lds + PG8_SA(b, h) + aoff + m * 2048 + k * 1024); } while (0)
; #define PG8_MMA(ai, bj, At, Bt) do { __builtin_amdgcn_s_setprio(1); _Pragma("unroll") for (int m = 0; m < 4; ++m) _Pragma("unroll") for (int n = 0; n < 2; ++n) _Pragma("unroll") for (int k = 0; k < 2; ++k) \
;         acc[ai][bj][m][n] = __builtin_amdgcn_mfma_f32_16x16x32_bf16(Bt[n][k], At[m][k], acc[ai][bj][m][n], 0, 0, 0); __builtin_amdgcn_s_setprio(0); } while (0)
; #define PG8_WAIT_V(n) asm volatile("s_waitcnt vmcnt(" #n ")" ::: "memory")
; #define PG8_WAIT_L(n) asm volatile("s_waitcnt lgkmcnt(" #n ")" ::: "memory")
; #define PG8_BAR __builtin_amdgcn_s_barrier()
; #define PG8_SCHED __builtin_amdgcn_sched_barrier(0)
; template <class Epi, class Sched, bool ALIGN_EPI = false, bool SP2 = false>
; __device__ __forceinline__ void gemm_phase(PG8_LAS unsigned char* lds, const Gemm g, const Sched& S, const Epi& E, const int wid_) {
;     ...
;             PG8_WAIT_V(8); PG8_WAIT_L(0); PG8_BAR; PG8_MMA(0, 0, At, B0); PG8_MMA(0, 1, At, B1); PG8_BAR; PG8_SCHED;
;             PG8_LDA(At, 1, 1); PG8_STAGE(PG8_SB(1, 0), b3, voffB); PG8_STAGE(PG8_SB(1, 1), b3 + hstepB, voffB); PG8_STAGE(PG8_SA(1, 0), a3, voffA);
;             PG8_WAIT_V(8); PG8_WAIT_L(0); PG8_BAR; PG8_MMA(1, 0, At, B0); PG8_MMA(1, 1, At, B1); PG8_BAR; PG8_SCHED;
;     ...
;         if constexpr (ALIGN_EPI) { if (wr == 0) PG8_BAR; }
	s_waitcnt lgkmcnt(0)
	v_mfma_f32_16x16x32_bf16 v[124:127], v[128:131], v[190:193], v[124:127]
	v_mfma_f32_16x16x32_bf16 v[120:123], v[136:139], v[190:193], v[120:123]
	v_mfma_f32_16x16x32_bf16 v[116:119], v[128:131], v[198:201], v[116:119]
	v_mfma_f32_16x16x32_bf16 v[112:115], v[136:139], v[198:201], v[112:115]
	v_mfma_f32_16x16x32_bf16 v[100:103], v[128:131], v[206:209], v[100:103]
	v_mfma_f32_16x16x32_bf16 v[96:99], v[136:139], v[206:209], v[96:99]
	v_mfma_f32_16x16x32_bf16 v[84:87], v[128:131], v[216:219], v[84:87]
	v_mfma_f32_16x16x32_bf16 v[80:83], v[136:139], v[216:219], v[80:83]
	v_mfma_f32_16x16x32_bf16 v[124:127], v[132:135], v[194:197], v[124:127]
	v_mfma_f32_16x16x32_bf16 v[120:123], v[164:167], v[194:197], v[120:123]
	v_mfma_f32_16x16x32_bf16 v[116:119], v[132:135], v[202:205], v[116:119]
	v_mfma_f32_16x16x32_bf16 v[112:115], v[164:167], v[202:205], v[112:115]
	v_mfma_f32_16x16x32_bf16 v[100:103], v[132:135], v[212:215], v[100:103]
	v_mfma_f32_16x16x32_bf16 v[96:99], v[164:167], v[212:215], v[96:99]
	v_mfma_f32_16x16x32_bf16 v[84:87], v[132:135], v[220:223], v[84:87]
	v_mfma_f32_16x16x32_bf16 v[80:83], v[164:167], v[220:223], v[80:83]
	v_mfma_f32_16x16x32_bf16 v[108:111], v[168:171], v[190:193], v[108:111]
	v_mfma_f32_16x16x32_bf16 v[104:107], v[182:185], v[190:193], v[104:107]
	v_mfma_f32_16x16x32_bf16 v[92:95], v[168:171], v[198:201], v[92:95]
	v_mfma_f32_16x16x32_bf16 v[88:91], v[182:185], v[198:201], v[88:91]
	v_mfma_f32_16x16x32_bf16 v[76:79], v[168:171], v[206:209], v[76:79]
	v_mfma_f32_16x16x32_bf16 v[72:75], v[182:185], v[206:209], v[72:75]
	v_mfma_f32_16x16x32_bf16 v[68:71], v[168:171], v[216:219], v[68:71]
	v_mfma_f32_16x16x32_bf16 v[64:67], v[182:185], v[216:219], v[64:67]
	v_mfma_f32_16x16x32_bf16 v[108:111], v[172:175], v[194:197], v[108:111]
	v_mfma_f32_16x16x32_bf16 v[104:107], v[186:189], v[194:197], v[104:107]
	v_mfma_f32_16x16x32_bf16 v[92:95], v[172:175], v[202:205], v[92:95]
	v_mfma_f32_16x16x32_bf16 v[88:91], v[186:189], v[202:205], v[88:91]
	v_mfma_f32_16x16x32_bf16 v[76:79], v[172:175], v[212:215], v[76:79]
	v_mfma_f32_16x16x32_bf16 v[72:75], v[186:189], v[212:215], v[72:75]
	v_mfma_f32_16x16x32_bf16 v[68:71], v[172:175], v[220:223], v[68:71]
	v_mfma_f32_16x16x32_bf16 v[64:67], v[186:189], v[220:223], v[64:67]
	s_barrier
	s_add_i32 s38, s98, s83
	v_lshl_add_u64 v[178:179], v[178:179], 0, s[66:67]
	s_mov_b32 m0, s38
	ds_read_b128 v[190:193], v181 offset:49152
	ds_read_b128 v[194:197], v181 offset:50176
	ds_read_b128 v[198:201], v181 offset:51200
	ds_read_b128 v[202:205], v181 offset:52224
	ds_read_b128 v[206:209], v181 offset:53248
	ds_read_b128 v[212:215], v181 offset:54272
	ds_read_b128 v[216:219], v181 offset:55296
	ds_read_b128 v[220:223], v181 offset:56320
	global_load_lds_dwordx4 v[178:179], off
	v_lshl_add_u64 v[178:179], v[224:225], 0, s[66:67]
	s_add_i32 m0, s38, 0x2000
	s_add_i32 s38, s99, s83
	global_load_lds_dwordx4 v[178:179], off
	v_lshl_add_u64 v[178:179], v[226:227], 0, s[66:67]
	s_mov_b32 m0, s38
	s_nop 0
	global_load_lds_dwordx4 v[178:179], off
	v_lshl_add_u64 v[178:179], v[228:229], 0, s[66:67]
	s_add_i32 m0, s38, 0x2000
	s_nop 0
	global_load_lds_dwordx4 v[178:179], off
	v_lshl_add_u64 v[178:179], v[230:231], 0, s[66:67]
	s_mov_b32 m0, s33
	s_nop 0
	global_load_lds_dwordx4 v[178:179], off
	v_lshl_add_u64 v[178:179], v[232:233], 0, s[66:67]
	s_mov_b32 m0, s52
	s_nop 0
	global_load_lds_dwordx4 v[178:179], off
	s_waitcnt vmcnt(8)
	s_waitcnt lgkmcnt(0)
	s_barrier
	s_waitcnt lgkmcnt(0)
	v_mfma_f32_16x16x32_bf16 v[60:63], v[128:131], v[190:193], v[60:63]
	v_mfma_f32_16x16x32_bf16 v[56:59], v[136:139], v[190:193], v[56:59]
	v_mfma_f32_16x16x32_bf16 v[52:55], v[128:131], v[198:201], v[52:55]
	v_mfma_f32_16x16x32_bf16 v[48:51], v[136:139], v[198:201], v[48:51]
	v_mfma_f32_16x16x32_bf16 v[36:39], v[128:131], v[206:209], v[36:39]
	v_mfma_f32_16x16x32_bf16 v[32:35], v[136:139], v[206:209], v[32:35]
	v_mfma_f32_16x16x32_bf16 v[20:23], v[128:131], v[216:219], v[20:23]
	v_mfma_f32_16x16x32_bf16 v[16:19], v[136:139], v[216:219], v[16:19]
	v_mfma_f32_16x16x32_bf16 v[60:63], v[132:135], v[194:197], v[60:63]
	v_mfma_f32_16x16x32_bf16 v[56:59], v[164:167], v[194:197], v[56:59]
	v_mfma_f32_16x16x32_bf16 v[52:55], v[132:135], v[202:205], v[52:55]
	v_mfma_f32_16x16x32_bf16 v[48:51], v[164:167], v[202:205], v[48:51]
	v_mfma_f32_16x16x32_bf16 v[36:39], v[132:135], v[212:215], v[36:39]
	v_mfma_f32_16x16x32_bf16 v[32:35], v[164:167], v[212:215], v[32:35]
	v_mfma_f32_16x16x32_bf16 v[20:23], v[132:135], v[220:223], v[20:23]
	v_mfma_f32_16x16x32_bf16 v[16:19], v[164:167], v[220:223], v[16:19]
	v_mfma_f32_16x16x32_bf16 v[44:47], v[168:171], v[190:193], v[44:47]
	v_mfma_f32_16x16x32_bf16 v[40:43], v[182:185], v[190:193], v[40:43]
	v_mfma_f32_16x16x32_bf16 v[28:31], v[168:171], v[198:201], v[28:31]
	v_mfma_f32_16x16x32_bf16 v[24:27], v[182:185], v[198:201], v[24:27]
	v_mfma_f32_16x16x32_bf16 v[12:15], v[168:171], v[206:209], v[12:15]
	v_mfma_f32_16x16x32_bf16 v[8:11], v[182:185], v[206:209], v[8:11]
	v_mfma_f32_16x16x32_bf16 v[4:7], v[168:171], v[216:219], v[4:7]
	v_mfma_f32_16x16x32_bf16 v[0:3], v[182:185], v[216:219], v[0:3]
	v_mfma_f32_16x16x32_bf16 v[44:47], v[172:175], v[194:197], v[44:47]
	v_mfma_f32_16x16x32_bf16 v[40:43], v[186:189], v[194:197], v[40:43]
	v_mfma_f32_16x16x32_bf16 v[28:31], v[172:175], v[202:205], v[28:31]
	v_mfma_f32_16x16x32_bf16 v[24:27], v[186:189], v[202:205], v[24:27]
	v_mfma_f32_16x16x32_bf16 v[12:15], v[172:175], v[212:215], v[12:15]
	v_mfma_f32_16x16x32_bf16 v[8:11], v[186:189], v[212:215], v[8:11]
	v_mfma_f32_16x16x32_bf16 v[4:7], v[172:175], v[220:223], v[4:7]
	v_mfma_f32_16x16x32_bf16 v[0:3], v[186:189], v[220:223], v[0:3]
	s_barrier
	s_add_u32 s49, s49, 0x100
	s_addc_u32 s62, s62, 0
	s_add_u32 s6, s6, 0x100
	s_addc_u32 s7, s7, 0
	s_cmp_ge_u32 s97, s71
	s_mov_b32 s38, s97
	s_cbranch_scc0 .LBB0_380
	s_setprio 0
	s_and_b64 vcc, exec, s[94:95]
	s_cbranch_vccz .LBB0_384
	s_barrier
	v_lshl_add_u32 v164, s48, 8, v153
	s_cmp_lt_i32 s37, 2
	s_mov_b64 s[6:7], -1
	s_cbranch_scc0 .LBB0_385

; template <class Epi, class Sched, bool ALIGN_EPI = false, bool SP2 = false>
; __device__ __forceinline__ void gemm_phase(PG8_LAS unsigned char* lds, const Gemm g, const Sched& S, const Epi& E, const int wid_) {
;     ...
; #pragma unroll
;         for (int a = 0; a < 2; ++a)
; #pragma unroll
;             for (int b = 0; b < 2; ++b)
; #pragma unroll
;                 for (int m = 0; m < 4; ++m)
; #pragma unroll
;                     for (int n = 0; n < 2; ++n) acc[a][b][m][n] = (f32x4){0.f, 0.f, 0.f, 0.f};
;         cur = nxt; cA = nA; cB = nB; ++ui;
.LBB0_613:
	s_add_u32 s11, s8, 0x100
	s_addc_u32 s76, s9, 0
	s_add_u32 s6, s38, 0x80
	s_addc_u32 s7, s39, 0
	s_mov_b32 s8, 0
	s_and_b64 vcc, exec, s[36:37]
	s_cbranch_vccnz .Lprio_b
	s_setprio 1
.Lprio_b:
	v_mov_b64_e32 v[0:1], 0
	v_mov_b64_e32 v[2:3], 0
	v_mov_b64_e32 v[4:5], 0
	v_mov_b64_e32 v[6:7], 0
	v_mov_b64_e32 v[8:9], 0
	v_mov_b64_e32 v[10:11], 0
	v_mov_b64_e32 v[12:13], 0
	v_mov_b64_e32 v[14:15], 0
	v_mov_b64_e32 v[16:17], 0
	v_mov_b64_e32 v[18:19], 0
	v_mov_b64_e32 v[20:21], 0
	v_mov_b64_e32 v[22:23], 0
	v_mov_b64_e32 v[24:25], 0
	v_mov_b64_e32 v[26:27], 0
	v_mov_b64_e32 v[28:29], 0
	v_mov_b64_e32 v[30:31], 0
	v_mov_b64_e32 v[32:33], 0
	v_mov_b64_e32 v[34:35], 0
	v_mov_b64_e32 v[36:37], 0
	v_mov_b64_e32 v[38:39], 0
	v_mov_b64_e32 v[40:41], 0
	v_mov_b64_e32 v[42:43], 0
	v_mov_b64_e32 v[44:45], 0
	v_mov_b64_e32 v[46:47], 0
	v_mov_b64_e32 v[48:49], 0
	v_mov_b64_e32 v[50:51], 0
	v_mov_b64_e32 v[52:53], 0
	v_mov_b64_e32 v[54:55], 0
	v_mov_b64_e32 v[56:57], 0
	v_mov_b64_e32 v[58:59], 0
	v_mov_b64_e32 v[60:61], 0
	v_mov_b64_e32 v[62:63], 0
	v_mov_b64_e32 v[64:65], 0
	v_mov_b64_e32 v[66:67], 0
	v_mov_b64_e32 v[68:69], 0
	v_mov_b64_e32 v[70:71], 0
	v_mov_b64_e32 v[72:73], 0
	v_mov_b64_e32 v[74:75], 0
	v_mov_b64_e32 v[76:77], 0
	v_mov_b64_e32 v[78:79], 0
	v_mov_b64_e32 v[80:81], 0
	v_mov_b64_e32 v[82:83], 0
	v_mov_b64_e32 v[84:85], 0
	v_mov_b64_e32 v[86:87], 0
	v_mov_b64_e32 v[88:89], 0
	v_mov_b64_e32 v[90:91], 0
	v_mov_b64_e32 v[92:93], 0
	v_mov_b64_e32 v[94:95], 0
	v_mov_b64_e32 v[96:97], 0
	v_mov_b64_e32 v[98:99], 0
	v_mov_b64_e32 v[100:101], 0
	v_mov_b64_e32 v[102:103], 0
	v_mov_b64_e32 v[108:109], 0
	v_mov_b64_e32 v[110:111], 0
	v_mov_b64_e32 v[116:117], 0
	v_mov_b64_e32 v[118:119], 0
	v_mov_b64_e32 v[120:121], 0
	v_mov_b64_e32 v[122:123], 0
	v_mov_b64_e32 v[128:129], 0
	v_mov_b64_e32 v[130:131], 0
	v_mov_b64_e32 v[136:137], 0
	v_mov_b64_e32 v[138:139], 0
	v_mov_b64_e32 v[140:141], 0
	v_mov_b64_e32 v[142:143], 0
